# attention: non-deferred waves issue K-fragment LDS reads at the top of the iteration, deferred waves before their deferred PV
# speedup vs baseline: 1.0056x; 1.0056x over previous
; #define LAS __attribute__((address_space(3)))
; DEV void attn_tile(LAS unsigned char* lds, const bf16x8 (&qf)[2][2], int tl, int kpos0, int mode, bool near, bool rowsel, const float (&cbias)[2],
;                    unsigned kb, unsigned vb_, unsigned btb, int g4, float (&mrun)[2], float (&lrun)[2], f32x4 (&O)[2][4]) {
;     ...
;         for (int kt = 0; kt < 4; ++kt) { kf[kt][0] = *(const LAS bf16x8*)(lds + kb + kt * 2304); kf[kt][1] = *(const LAS bf16x8*)(lds + kb + kt * 2304 + 64); }
; DEV void attn_item(LAS unsigned char* lds, const bf16_t* P, const bf16_t* QB, const bf16_t* KV, const bf16_t* KC, const bf16_t* VC, const float* rel_bias, bf16_t* OB, int b, int g, int qt) {
;     ...
;         for (;;) {
;             kv_store(lds, pre, buf, tid);
;             __syncthreads();
;             int mode_n = mode, j_n = 0; bool more = true;
;             if (mode == 1) { if (rem != 0u) { j_n = __builtin_ctz(rem); rem &= rem - 1u; } else { mode_n = 2; j_n = max(0, qt - 8); } }
;             else { j_n = j + 1; more = j_n <= qt; }
;             if (more) { const bf16_t* base = pbg + (size_t)j_n * 64 * 64 + (mode_n == 1 ? 2 : 4) * KV_TENSOR; pre = kv_fetch(base, base + KV_TENSOR, tid); }
;             const bool near = (j >= qt - 2) || (mode == 2 && j == qt - 8);
.LBB0_260:
	s_cmp_eq_u32 s100, 1
	s_cbranch_scc1 .Lst_kskip
	v_add_u32_e32 v228, s98, v141
	ds_read_b128 v[72:75], v228
	ds_read_b128 v[76:79], v228 offset:64
	ds_read_b128 v[80:83], v228 offset:2304
	ds_read_b128 v[84:87], v228 offset:2368
	ds_read_b128 v[88:91], v228 offset:4608
	ds_read_b128 v[154:157], v228 offset:4672
	ds_read_b128 v[92:95], v228 offset:6912
	ds_read_b128 v[158:161], v228 offset:6976

; #define LAS __attribute__((address_space(3)))
; DEV void attn_tile(LAS unsigned char* lds, const bf16x8 (&qf)[2][2], int tl, int kpos0, int mode, bool near, bool rowsel, const float (&cbias)[2],
;                    unsigned kb, unsigned vb_, unsigned btb, int g4, float (&mrun)[2], float (&lrun)[2], f32x4 (&O)[2][4]) {
;     f32x4 sc[2][4];
;     float ci[2];
; #pragma unroll
;     for (int hh = 0; hh < 2; ++hh) { const float mne = mrun[hh] < -1e29f ? 0.f : mrun[hh];
;         ci[hh] = near ? -mne : (((mode == 1 && !rowsel) ? NEG_ : cbias[hh]) - mne); }
;     {
;         bf16x8 kf[4][2];
; #pragma unroll
;         for (int kt = 0; kt < 4; ++kt) { kf[kt][0] = *(const LAS bf16x8*)(lds + kb + kt * 2304); kf[kt][1] = *(const LAS bf16x8*)(lds + kb + kt * 2304 + 64); }
;         __builtin_amdgcn_sched_barrier(0);
; #pragma unroll
;         for (int kt = 0; kt < 4; ++kt)
; #pragma unroll
;             for (int hh = 0; hh < 2; ++hh) sc[hh][kt] = __builtin_amdgcn_mfma_f32_16x16x32_bf16(kf[kt][0], qf[hh][0], (f32x4){ci[hh], ci[hh], ci[hh], ci[hh]}, 0, 0, 0);
; #pragma unroll
;         for (int kt = 0; kt < 4; ++kt)
; #pragma unroll
;             for (int hh = 0; hh < 2; ++hh) sc[hh][kt] = __builtin_amdgcn_mfma_f32_16x16x32_bf16(kf[kt][1], qf[hh][1], sc[hh][kt], 0, 0, 0);
;     }
.Lst_xx:
	s_mov_b32 s101, s99
	s_cmp_ge_i32 s50, s36
	s_cselect_b64 s[4:5], -1, 0
	s_cmp_eq_u32 s97, 2
	s_cselect_b64 s[6:7], -1, 0
	s_cmp_eq_u32 s50, s17
	s_cselect_b64 s[42:43], -1, 0
	s_and_b64 s[6:7], s[6:7], s[42:43]
	s_or_b64 s[4:5], s[4:5], s[6:7]
	v_lshrrev_b32_e32 v64, s50, v127
	v_and_b32_e32 v64, 1, v64
	s_cmp_lg_u32 s97, 1
	v_cmp_eq_u32_e64 s[48:49], 1, v64
	s_cselect_b64 s[6:7], -1, 0
	s_or_b64 vcc, s[6:7], s[48:49]
	v_cmp_gt_f32_e64 s[44:45], s65, v149
	v_cndmask_b32_e32 v65, v223, v136, vcc
	v_cmp_gt_f32_e64 s[42:43], s65, v150
	v_cndmask_b32_e64 v64, v149, 0, s[44:45]
	v_sub_f32_e32 v65, v65, v64
	v_cndmask_b32_e64 v64, v65, -v64, s[4:5]
	v_cndmask_b32_e64 v65, v150, 0, s[42:43]
	v_cndmask_b32_e32 v66, v223, v137, vcc
	v_sub_f32_e32 v66, v66, v65
	v_cndmask_b32_e64 v68, v66, -v65, s[4:5]
	v_mov_b32_e32 v65, v64
	v_mov_b32_e32 v66, v64
	v_mov_b32_e32 v67, v64
	v_mov_b32_e32 v69, v68
	v_mov_b32_e32 v70, v68
	v_mov_b32_e32 v71, v68
	s_waitcnt lgkmcnt(7)
	v_mfma_f32_16x16x32_bf16 v[162:165], v[72:75], v[8:11], v[64:67]
	s_mov_b64 s[6:7], -1
	s_and_b64 vcc, exec, s[4:5]
	v_mfma_f32_16x16x32_bf16 v[72:75], v[72:75], v[16:19], v[68:71]
	v_add_u32_e32 v228, s98, v145
	v_add_u32_e32 v229, 0x800, v228
	v_add_u32_e32 v230, 0x1000, v228
	v_add_u32_e32 v231, 0x1800, v228
	ds_read2_b64 v[232:235], v228 offset1:4
	ds_read2_b64 v[236:239], v228 offset0:8 offset1:12
	ds_read2_b64 v[240:243], v229 offset0:32 offset1:36
	ds_read2_b64 v[244:247], v229 offset0:40 offset1:44
	ds_read2_b64 v[248:251], v230 offset0:64 offset1:68
	ds_read2_b64 v[198:201], v230 offset0:72 offset1:76
	ds_read2_b64 v[202:205], v231 offset0:96 offset1:100
	ds_read2_b64 v[206:209], v231 offset0:104 offset1:108
	s_waitcnt lgkmcnt(13)
	v_mfma_f32_16x16x32_bf16 v[166:169], v[80:83], v[8:11], v[64:67]
	v_mfma_f32_16x16x32_bf16 v[80:83], v[80:83], v[16:19], v[68:71]
	s_waitcnt lgkmcnt(11)
	v_mfma_f32_16x16x32_bf16 v[180:183], v[88:91], v[8:11], v[64:67]
	v_mfma_f32_16x16x32_bf16 v[184:187], v[88:91], v[16:19], v[68:71]
	s_waitcnt lgkmcnt(9)
	v_mfma_f32_16x16x32_bf16 v[188:191], v[92:95], v[8:11], v[64:67]
	v_mfma_f32_16x16x32_bf16 v[68:71], v[92:95], v[16:19], v[68:71]
	v_mfma_f32_16x16x32_bf16 v[92:95], v[76:79], v[12:15], v[162:165]
	v_mfma_f32_16x16x32_bf16 v[76:79], v[76:79], v[20:23], v[72:75]
	v_mfma_f32_16x16x32_bf16 v[88:91], v[84:87], v[12:15], v[166:169]
	v_mfma_f32_16x16x32_bf16 v[72:75], v[84:87], v[20:23], v[80:83]
	v_mfma_f32_16x16x32_bf16 v[84:87], v[154:157], v[12:15], v[180:183]
	v_mfma_f32_16x16x32_bf16 v[64:67], v[154:157], v[20:23], v[184:187]
	s_waitcnt lgkmcnt(8)
	v_mfma_f32_16x16x32_bf16 v[80:83], v[158:161], v[12:15], v[188:191]
	v_mfma_f32_16x16x32_bf16 v[68:71], v[158:161], v[20:23], v[68:71]
	s_cbranch_vccnz .LBB0_271
	s_mov_b64 s[6:7], 0
